# fused GEMM2 and GEMM4 LayerNorm epilogues: residual tile loads issued in bursts into dead operand registers instead of one dependent round trip per row group; top-k compare/select chains interleaved
# speedup vs baseline: 1.0009x; 1.0009x over previous
.LBB0_1922:
	s_ashr_i32 s0, s12, 31
	s_lshr_b32 s0, s0, 27
	s_add_i32 s0, s12, s0
	s_ashr_i32 s0, s0, 5
	s_mul_i32 s0, s0, 3
	s_ashr_i32 s1, s0, 31
	s_lshl_b32 s14, s13, 5
	s_lshl_b64 s[0:1], s[0:1], 12
	s_add_u32 s0, s62, s0
	s_addc_u32 s1, s63, s1
	s_add_u32 s4, s0, 0x68000
	s_addc_u32 s5, s1, 0
	s_lshl_b32 s0, s6, 8
	v_lshrrev_b32_e32 v130, 1, v160
	s_or_b32 s0, s0, s14
	s_lshl_b32 s24, s12, 8
	v_and_or_b32 v134, v130, 24, s0
	s_add_i32 s0, s24, s41
	v_or_b32_e32 v132, s0, v161
	v_ashrrev_i32_e32 v135, 31, v134
	v_lshl_add_u64 v[130:131], v[134:135], 2, s[4:5]
	v_ashrrev_i32_e32 v133, 31, v132
	s_barrier
	global_load_dwordx4 v[146:149], v[130:131], off offset:16
	global_load_dwordx4 v[140:143], v[130:131], off
	v_lshlrev_b64 v[130:131], 11, v[132:133]
	v_lshl_add_u64 v[130:131], s[76:77], 0, v[130:131]
	v_lshlrev_b64 v[150:151], 1, v[134:135]
	v_lshl_add_u64 v[136:137], v[130:131], 0, v[150:151]
	global_load_dwordx4 v[172:175], v[136:137], off
	s_mov_b64 s[98:99], 0x8000
	v_lshl_add_u64 v[236:237], v[136:137], 0, s[98:99]
	s_mov_b64 s[98:99], 0x10000
	v_lshl_add_u64 v[238:239], v[136:137], 0, s[98:99]
	s_mov_b64 s[98:99], 0x18000
	v_lshl_add_u64 v[242:243], v[136:137], 0, s[98:99]
	s_mov_b64 s[98:99], 0x40000
	v_lshl_add_u64 v[244:245], v[136:137], 0, s[98:99]
	s_mov_b64 s[98:99], 0x48000
	v_lshl_add_u64 v[246:247], v[136:137], 0, s[98:99]
	s_mov_b64 s[98:99], 0x50000
	v_lshl_add_u64 v[248:249], v[136:137], 0, s[98:99]
	s_mov_b64 s[98:99], 0x58000
	v_lshl_add_u64 v[250:251], v[136:137], 0, s[98:99]
	global_load_dwordx4 v[176:179], v[236:237], off
	global_load_dwordx4 v[180:183], v[238:239], off
	global_load_dwordx4 v[184:187], v[242:243], off
	global_load_dwordx4 v[188:191], v[244:245], off
	global_load_dwordx4 v[192:195], v[246:247], off
	global_load_dwordx4 v[196:199], v[248:249], off
	global_load_dwordx4 v[200:203], v[250:251], off
	global_load_dwordx4 v[204:207], v[136:137], off offset:256
	global_load_dwordx4 v[208:211], v[236:237], off offset:256
	global_load_dwordx4 v[212:215], v[238:239], off offset:256
	global_load_dwordx4 v[216:219], v[242:243], off offset:256
	global_load_dwordx4 v[220:223], v[244:245], off offset:256
	global_load_dwordx4 v[224:227], v[246:247], off offset:256
	global_load_dwordx4 v[228:231], v[248:249], off offset:256
	v_or_b32_e32 v130, 16, v132
	v_ashrrev_i32_e32 v131, 31, v130
	v_lshlrev_b64 v[130:131], 11, v[130:131]
	v_lshl_add_u64 v[130:131], s[76:77], 0, v[130:131]
	s_mov_b32 s0, 0x3fb504f3
	v_lshl_add_u64 v[138:139], v[130:131], 0, v[150:151]
	s_waitcnt vmcnt(14)
	v_pk_add_f32 v[144:145], v[148:149], 1.0 op_sel_hi:[1,0]
	v_pk_add_f32 v[130:131], v[142:143], 1.0 op_sel_hi:[1,0]
	v_pk_add_f32 v[142:143], v[140:141], 1.0 op_sel_hi:[1,0]
	v_pk_add_f32 v[146:147], v[146:147], 1.0 op_sel_hi:[1,0]
	v_lshlrev_b32_e32 v140, 16, v172
	v_and_b32_e32 v141, 0xffff0000, v172
	v_lshlrev_b32_e32 v148, 16, v173
	v_and_b32_e32 v149, 0xffff0000, v173
	v_lshlrev_b32_e32 v152, 16, v174
	v_and_b32_e32 v153, 0xffff0000, v174
	v_lshlrev_b32_e32 v154, 16, v175
	v_and_b32_e32 v155, 0xffff0000, v175
	v_pk_mul_f32 v[140:141], v[140:141], s[0:1] op_sel_hi:[1,0]
	v_pk_mul_f32 v[148:149], v[148:149], s[0:1] op_sel_hi:[1,0]
	v_pk_mul_f32 v[152:153], v[152:153], s[0:1] op_sel_hi:[1,0]
	v_pk_mul_f32 v[154:155], v[154:155], s[0:1] op_sel_hi:[1,0]
	v_pk_fma_f32 v[72:73], v[72:73], v[130:131], v[148:149]
	v_pk_fma_f32 v[70:71], v[70:71], v[142:143], v[140:141]
	v_pk_fma_f32 v[68:69], v[68:69], v[144:145], v[154:155]
	v_pk_fma_f32 v[66:67], v[66:67], v[146:147], v[152:153]
	v_or_b32_e32 v140, 32, v132
	v_ashrrev_i32_e32 v141, 31, v140
	v_lshlrev_b64 v[140:141], 11, v[140:141]
	v_lshl_add_u64 v[140:141], s[76:77], 0, v[140:141]
	v_lshl_add_u64 v[140:141], v[140:141], 0, v[150:151]
	s_waitcnt vmcnt(13)
	v_lshlrev_b32_e32 v148, 16, v176
	v_and_b32_e32 v149, 0xffff0000, v176
	v_lshlrev_b32_e32 v152, 16, v177
	v_and_b32_e32 v153, 0xffff0000, v177
	v_lshlrev_b32_e32 v156, 16, v178
	v_and_b32_e32 v157, 0xffff0000, v178
	v_lshlrev_b32_e32 v154, 16, v179
	v_and_b32_e32 v155, 0xffff0000, v179
	v_pk_mul_f32 v[148:149], v[148:149], s[0:1] op_sel_hi:[1,0]
	v_pk_mul_f32 v[152:153], v[152:153], s[0:1] op_sel_hi:[1,0]
	v_pk_mul_f32 v[156:157], v[156:157], s[0:1] op_sel_hi:[1,0]
	v_pk_mul_f32 v[154:155], v[154:155], s[0:1] op_sel_hi:[1,0]
	v_pk_fma_f32 v[88:89], v[88:89], v[130:131], v[152:153]
	v_pk_fma_f32 v[86:87], v[86:87], v[142:143], v[148:149]
	v_pk_fma_f32 v[84:85], v[84:85], v[144:145], v[154:155]
	v_pk_fma_f32 v[82:83], v[82:83], v[146:147], v[156:157]
	v_or_b32_e32 v148, 48, v132
	v_ashrrev_i32_e32 v149, 31, v148
	v_lshlrev_b64 v[148:149], 11, v[148:149]
	v_lshl_add_u64 v[148:149], s[76:77], 0, v[148:149]
	v_lshl_add_u64 v[148:149], v[148:149], 0, v[150:151]
	s_waitcnt vmcnt(12)
	v_lshlrev_b32_e32 v156, 16, v180
	v_and_b32_e32 v157, 0xffff0000, v180
	v_lshlrev_b32_e32 v152, 16, v181
	v_and_b32_e32 v153, 0xffff0000, v181
	v_lshlrev_b32_e32 v158, 16, v182
	v_and_b32_e32 v159, 0xffff0000, v182
	v_lshlrev_b32_e32 v154, 16, v183
	v_and_b32_e32 v155, 0xffff0000, v183
	v_pk_mul_f32 v[156:157], v[156:157], s[0:1] op_sel_hi:[1,0]
	v_pk_mul_f32 v[152:153], v[152:153], s[0:1] op_sel_hi:[1,0]
	v_pk_mul_f32 v[158:159], v[158:159], s[0:1] op_sel_hi:[1,0]
	v_pk_mul_f32 v[154:155], v[154:155], s[0:1] op_sel_hi:[1,0]
	v_pk_fma_f32 v[104:105], v[104:105], v[130:131], v[152:153]
	v_pk_fma_f32 v[102:103], v[102:103], v[142:143], v[156:157]
	v_pk_fma_f32 v[100:101], v[100:101], v[144:145], v[154:155]
	v_pk_fma_f32 v[98:99], v[98:99], v[146:147], v[158:159]
	v_add_u32_e32 v152, 0x80, v132
	v_ashrrev_i32_e32 v153, 31, v152
	v_lshlrev_b64 v[152:153], 11, v[152:153]
	v_lshl_add_u64 v[152:153], s[76:77], 0, v[152:153]
	v_lshl_add_u64 v[152:153], v[152:153], 0, v[150:151]
	s_waitcnt vmcnt(11)
	v_lshlrev_b32_e32 v158, 16, v184
	v_and_b32_e32 v159, 0xffff0000, v184
	v_lshlrev_b32_e32 v154, 16, v185
	v_and_b32_e32 v155, 0xffff0000, v185
	v_lshlrev_b32_e32 v162, 16, v186
	v_and_b32_e32 v163, 0xffff0000, v186
	v_lshlrev_b32_e32 v156, 16, v187
	v_and_b32_e32 v157, 0xffff0000, v187
	v_pk_mul_f32 v[158:159], v[158:159], s[0:1] op_sel_hi:[1,0]
	v_pk_mul_f32 v[154:155], v[154:155], s[0:1] op_sel_hi:[1,0]
	v_pk_mul_f32 v[162:163], v[162:163], s[0:1] op_sel_hi:[1,0]
	v_pk_mul_f32 v[156:157], v[156:157], s[0:1] op_sel_hi:[1,0]
	v_pk_fma_f32 v[112:113], v[112:113], v[130:131], v[154:155]
	v_pk_fma_f32 v[110:111], v[110:111], v[142:143], v[158:159]
	v_pk_fma_f32 v[108:109], v[108:109], v[144:145], v[156:157]
	v_pk_fma_f32 v[106:107], v[106:107], v[146:147], v[162:163]
	v_add_u32_e32 v154, 0x90, v132
	v_ashrrev_i32_e32 v155, 31, v154
	v_lshlrev_b64 v[154:155], 11, v[154:155]
	v_lshl_add_u64 v[154:155], s[76:77], 0, v[154:155]
	v_lshl_add_u64 v[156:157], v[154:155], 0, v[150:151]
	s_waitcnt vmcnt(10)
	v_lshlrev_b32_e32 v154, 16, v188
	v_and_b32_e32 v155, 0xffff0000, v188
	v_lshlrev_b32_e32 v158, 16, v189
	v_and_b32_e32 v159, 0xffff0000, v189
	v_lshlrev_b32_e32 v162, 16, v190
	v_and_b32_e32 v163, 0xffff0000, v190
	v_lshlrev_b32_e32 v164, 16, v191
	v_and_b32_e32 v165, 0xffff0000, v191
	v_pk_mul_f32 v[154:155], v[154:155], s[0:1] op_sel_hi:[1,0]
	v_pk_mul_f32 v[158:159], v[158:159], s[0:1] op_sel_hi:[1,0]
	v_pk_mul_f32 v[162:163], v[162:163], s[0:1] op_sel_hi:[1,0]
	v_pk_mul_f32 v[164:165], v[164:165], s[0:1] op_sel_hi:[1,0]
	v_pk_fma_f32 v[128:129], v[128:129], v[130:131], v[158:159]
	v_pk_fma_f32 v[126:127], v[126:127], v[142:143], v[154:155]
	v_pk_fma_f32 v[124:125], v[124:125], v[144:145], v[164:165]
	v_pk_fma_f32 v[122:123], v[122:123], v[146:147], v[162:163]
	v_add_u32_e32 v154, 0xa0, v132
	v_ashrrev_i32_e32 v155, 31, v154
	v_lshlrev_b64 v[154:155], 11, v[154:155]
	v_lshl_add_u64 v[154:155], s[76:77], 0, v[154:155]
	v_lshl_add_u64 v[158:159], v[154:155], 0, v[150:151]
	v_add_u32_e32 v132, 0xb0, v132
	v_ashrrev_i32_e32 v133, 31, v132
	v_lshlrev_b64 v[132:133], 11, v[132:133]
	v_lshl_add_u64 v[132:133], s[76:77], 0, v[132:133]
	v_lshl_add_u64 v[150:151], v[132:133], 0, v[150:151]
	s_waitcnt vmcnt(9)
	v_lshlrev_b32_e32 v154, 16, v192
	v_and_b32_e32 v155, 0xffff0000, v192
	v_lshlrev_b32_e32 v162, 16, v193
	v_and_b32_e32 v163, 0xffff0000, v193
	v_lshlrev_b32_e32 v166, 16, v194
	v_and_b32_e32 v167, 0xffff0000, v194
	v_lshlrev_b32_e32 v164, 16, v195
	v_and_b32_e32 v165, 0xffff0000, v195
	v_pk_mul_f32 v[154:155], v[154:155], s[0:1] op_sel_hi:[1,0]
	v_pk_mul_f32 v[162:163], v[162:163], s[0:1] op_sel_hi:[1,0]
	v_pk_mul_f32 v[166:167], v[166:167], s[0:1] op_sel_hi:[1,0]
	v_pk_mul_f32 v[164:165], v[164:165], s[0:1] op_sel_hi:[1,0]
	v_pk_fma_f32 v[120:121], v[120:121], v[130:131], v[162:163]
	v_pk_fma_f32 v[118:119], v[118:119], v[142:143], v[154:155]
	v_pk_fma_f32 v[116:117], v[116:117], v[144:145], v[164:165]
	v_pk_fma_f32 v[114:115], v[114:115], v[146:147], v[166:167]
	s_nop 0
	s_waitcnt vmcnt(8)
	v_lshlrev_b32_e32 v132, 16, v196
	v_and_b32_e32 v133, 0xffff0000, v196
	v_lshlrev_b32_e32 v154, 16, v197
	v_and_b32_e32 v155, 0xffff0000, v197
	v_lshlrev_b32_e32 v162, 16, v198
	v_and_b32_e32 v163, 0xffff0000, v198
	v_lshlrev_b32_e32 v164, 16, v199
	v_and_b32_e32 v165, 0xffff0000, v199
	v_pk_mul_f32 v[132:133], v[132:133], s[0:1] op_sel_hi:[1,0]
	v_pk_mul_f32 v[154:155], v[154:155], s[0:1] op_sel_hi:[1,0]
	v_pk_mul_f32 v[162:163], v[162:163], s[0:1] op_sel_hi:[1,0]
	v_pk_mul_f32 v[164:165], v[164:165], s[0:1] op_sel_hi:[1,0]
	v_pk_fma_f32 v[96:97], v[96:97], v[130:131], v[154:155]
	v_pk_fma_f32 v[94:95], v[94:95], v[142:143], v[132:133]
	v_pk_fma_f32 v[92:93], v[92:93], v[144:145], v[164:165]
	v_pk_fma_f32 v[90:91], v[90:91], v[146:147], v[162:163]
	v_or_b32_e32 v154, 0x80, v134
	v_ashrrev_i32_e32 v155, 31, v154
	v_lshl_add_u64 v[166:167], v[154:155], 2, s[4:5]
	s_waitcnt vmcnt(7)
	v_lshlrev_b32_e32 v132, 16, v200
	v_and_b32_e32 v133, 0xffff0000, v200
	v_lshlrev_b32_e32 v162, 16, v201
	v_and_b32_e32 v163, 0xffff0000, v201
	v_lshlrev_b32_e32 v168, 16, v202
	v_and_b32_e32 v169, 0xffff0000, v202
	v_lshlrev_b32_e32 v164, 16, v203
	v_and_b32_e32 v165, 0xffff0000, v203
	v_pk_mul_f32 v[170:171], v[132:133], s[0:1] op_sel_hi:[1,0]
	v_pk_mul_f32 v[132:133], v[162:163], s[0:1] op_sel_hi:[1,0]
	v_pk_mul_f32 v[162:163], v[168:169], s[0:1] op_sel_hi:[1,0]
	v_pk_mul_f32 v[164:165], v[164:165], s[0:1] op_sel_hi:[1,0]
	v_pk_fma_f32 v[132:133], v[60:61], v[130:131], v[132:133]
	v_pk_fma_f32 v[130:131], v[58:59], v[142:143], v[170:171]
	v_pk_fma_f32 v[60:61], v[56:57], v[144:145], v[164:165]
	v_pk_fma_f32 v[58:59], v[54:55], v[146:147], v[162:163]
	s_nop 0
	global_load_dwordx4 v[54:57], v[166:167], off
	global_load_dwordx4 v[162:165], v[166:167], off offset:16
	s_nop 0
	s_waitcnt vmcnt(1)
	v_pk_add_f32 v[136:137], v[56:57], 1.0 op_sel_hi:[1,0]
	v_pk_add_f32 v[142:143], v[54:55], 1.0 op_sel_hi:[1,0]
	s_waitcnt vmcnt(0)
	v_pk_add_f32 v[144:145], v[164:165], 1.0 op_sel_hi:[1,0]
	v_pk_add_f32 v[146:147], v[162:163], 1.0 op_sel_hi:[1,0]
	s_waitcnt vmcnt(0)
	v_lshlrev_b32_e32 v54, 16, v204
	v_and_b32_e32 v55, 0xffff0000, v204
	v_lshlrev_b32_e32 v56, 16, v205
	v_and_b32_e32 v57, 0xffff0000, v205
	v_lshlrev_b32_e32 v162, 16, v206
	v_and_b32_e32 v163, 0xffff0000, v206
	v_lshlrev_b32_e32 v164, 16, v207
	v_and_b32_e32 v165, 0xffff0000, v207
	v_pk_mul_f32 v[54:55], v[54:55], s[0:1] op_sel_hi:[1,0]
	v_pk_mul_f32 v[56:57], v[56:57], s[0:1] op_sel_hi:[1,0]
	v_pk_mul_f32 v[162:163], v[162:163], s[0:1] op_sel_hi:[1,0]
	v_pk_mul_f32 v[164:165], v[164:165], s[0:1] op_sel_hi:[1,0]
	v_pk_fma_f32 v[80:81], v[80:81], v[136:137], v[56:57]
	v_pk_fma_f32 v[78:79], v[78:79], v[142:143], v[54:55]
	v_pk_fma_f32 v[56:57], v[76:77], v[144:145], v[164:165]
	v_pk_fma_f32 v[54:55], v[74:75], v[146:147], v[162:163]
	s_nop 0
	s_waitcnt vmcnt(0)
	v_lshlrev_b32_e32 v138, 16, v208
	v_and_b32_e32 v139, 0xffff0000, v208
	v_lshlrev_b32_e32 v74, 16, v209
	v_and_b32_e32 v75, 0xffff0000, v209
	v_lshlrev_b32_e32 v162, 16, v210
	v_and_b32_e32 v163, 0xffff0000, v210
	v_lshlrev_b32_e32 v76, 16, v211
	v_and_b32_e32 v77, 0xffff0000, v211
	v_pk_mul_f32 v[138:139], v[138:139], s[0:1] op_sel_hi:[1,0]
	v_pk_mul_f32 v[74:75], v[74:75], s[0:1] op_sel_hi:[1,0]
	v_pk_mul_f32 v[162:163], v[162:163], s[0:1] op_sel_hi:[1,0]
	v_pk_mul_f32 v[76:77], v[76:77], s[0:1] op_sel_hi:[1,0]
	v_pk_fma_f32 v[64:65], v[64:65], v[136:137], v[74:75]
	v_pk_fma_f32 v[62:63], v[62:63], v[142:143], v[138:139]
	v_pk_fma_f32 v[52:53], v[52:53], v[144:145], v[76:77]
	v_pk_fma_f32 v[50:51], v[50:51], v[146:147], v[162:163]
	s_nop 0
	s_waitcnt vmcnt(0)
	v_lshlrev_b32_e32 v138, 16, v212
	v_and_b32_e32 v139, 0xffff0000, v212
	v_lshlrev_b32_e32 v74, 16, v213
	v_and_b32_e32 v75, 0xffff0000, v213
	v_lshlrev_b32_e32 v140, 16, v214
	v_and_b32_e32 v141, 0xffff0000, v214
	v_lshlrev_b32_e32 v76, 16, v215
	v_and_b32_e32 v77, 0xffff0000, v215
	v_pk_mul_f32 v[138:139], v[138:139], s[0:1] op_sel_hi:[1,0]
	v_pk_mul_f32 v[74:75], v[74:75], s[0:1] op_sel_hi:[1,0]
	v_pk_mul_f32 v[140:141], v[140:141], s[0:1] op_sel_hi:[1,0]
	v_pk_mul_f32 v[76:77], v[76:77], s[0:1] op_sel_hi:[1,0]
	v_pk_fma_f32 v[48:49], v[48:49], v[136:137], v[74:75]
	v_pk_fma_f32 v[46:47], v[46:47], v[142:143], v[138:139]
	v_pk_fma_f32 v[44:45], v[44:45], v[144:145], v[76:77]
	v_pk_fma_f32 v[42:43], v[42:43], v[146:147], v[140:141]
	s_nop 0
	s_waitcnt vmcnt(0)
	v_lshlrev_b32_e32 v138, 16, v216
	v_and_b32_e32 v139, 0xffff0000, v216
	v_lshlrev_b32_e32 v74, 16, v217
	v_and_b32_e32 v75, 0xffff0000, v217
	v_lshlrev_b32_e32 v140, 16, v218
	v_and_b32_e32 v141, 0xffff0000, v218
	v_lshlrev_b32_e32 v76, 16, v219
	v_and_b32_e32 v77, 0xffff0000, v219
	v_pk_mul_f32 v[138:139], v[138:139], s[0:1] op_sel_hi:[1,0]
	v_pk_mul_f32 v[74:75], v[74:75], s[0:1] op_sel_hi:[1,0]
	v_pk_mul_f32 v[140:141], v[140:141], s[0:1] op_sel_hi:[1,0]
	v_pk_mul_f32 v[76:77], v[76:77], s[0:1] op_sel_hi:[1,0]
	v_pk_fma_f32 v[40:41], v[40:41], v[136:137], v[74:75]
	v_pk_fma_f32 v[38:39], v[38:39], v[142:143], v[138:139]
	v_pk_fma_f32 v[36:37], v[36:37], v[144:145], v[76:77]
	v_pk_fma_f32 v[34:35], v[34:35], v[146:147], v[140:141]
	s_nop 0
	s_waitcnt vmcnt(0)
	v_lshlrev_b32_e32 v138, 16, v220
	v_and_b32_e32 v139, 0xffff0000, v220
	v_lshlrev_b32_e32 v74, 16, v221
	v_and_b32_e32 v75, 0xffff0000, v221
	v_lshlrev_b32_e32 v140, 16, v222
	v_and_b32_e32 v141, 0xffff0000, v222
	v_lshlrev_b32_e32 v76, 16, v223
	v_and_b32_e32 v77, 0xffff0000, v223
	v_pk_mul_f32 v[138:139], v[138:139], s[0:1] op_sel_hi:[1,0]
	v_pk_mul_f32 v[74:75], v[74:75], s[0:1] op_sel_hi:[1,0]
	v_pk_mul_f32 v[140:141], v[140:141], s[0:1] op_sel_hi:[1,0]
	v_pk_mul_f32 v[76:77], v[76:77], s[0:1] op_sel_hi:[1,0]
	v_pk_fma_f32 v[32:33], v[32:33], v[136:137], v[74:75]
	v_pk_fma_f32 v[30:31], v[30:31], v[142:143], v[138:139]
	v_pk_fma_f32 v[28:29], v[28:29], v[144:145], v[76:77]
	v_pk_fma_f32 v[26:27], v[26:27], v[146:147], v[140:141]
	s_nop 0
	s_waitcnt vmcnt(0)
	v_lshlrev_b32_e32 v138, 16, v224
	v_and_b32_e32 v139, 0xffff0000, v224
	v_lshlrev_b32_e32 v74, 16, v225
	v_and_b32_e32 v75, 0xffff0000, v225
	v_lshlrev_b32_e32 v140, 16, v226
	v_and_b32_e32 v141, 0xffff0000, v226
	v_lshlrev_b32_e32 v76, 16, v227
	v_and_b32_e32 v77, 0xffff0000, v227
	v_pk_mul_f32 v[138:139], v[138:139], s[0:1] op_sel_hi:[1,0]
	v_pk_mul_f32 v[74:75], v[74:75], s[0:1] op_sel_hi:[1,0]
	v_pk_mul_f32 v[140:141], v[140:141], s[0:1] op_sel_hi:[1,0]
	v_pk_mul_f32 v[76:77], v[76:77], s[0:1] op_sel_hi:[1,0]
	v_pk_fma_f32 v[24:25], v[24:25], v[136:137], v[74:75]
	v_pk_fma_f32 v[22:23], v[22:23], v[142:143], v[138:139]
	v_pk_fma_f32 v[20:21], v[20:21], v[144:145], v[76:77]
	v_pk_fma_f32 v[18:19], v[18:19], v[146:147], v[140:141]
	v_mbcnt_lo_u32_b32 v74, -1, 0
	v_mbcnt_hi_u32_b32 v75, -1, v74
	v_and_b32_e32 v76, 64, v75
	v_add_u32_e32 v156, 64, v76
	v_mov_b32_e32 v76, v71
	v_mov_b32_e32 v77, v72
	v_xor_b32_e32 v74, 16, v75
	v_cmp_lt_i32_e32 vcc, v74, v156
	s_waitcnt vmcnt(0)
	v_lshlrev_b32_e32 v148, 16, v228
	v_and_b32_e32 v149, 0xffff0000, v228
	v_lshlrev_b32_e32 v138, 16, v229
	v_and_b32_e32 v139, 0xffff0000, v229
	v_lshlrev_b32_e32 v152, 16, v230
	v_and_b32_e32 v153, 0xffff0000, v230
	v_lshlrev_b32_e32 v140, 16, v231
	v_and_b32_e32 v141, 0xffff0000, v231
	v_pk_mul_f32 v[148:149], v[148:149], s[0:1] op_sel_hi:[1,0]
	v_pk_mul_f32 v[138:139], v[138:139], s[0:1] op_sel_hi:[1,0]
	v_pk_mul_f32 v[152:153], v[152:153], s[0:1] op_sel_hi:[1,0]
	v_pk_mul_f32 v[140:141], v[140:141], s[0:1] op_sel_hi:[1,0]
	v_pk_fma_f32 v[16:17], v[16:17], v[136:137], v[138:139]
	v_pk_fma_f32 v[14:15], v[14:15], v[142:143], v[148:149]
	v_pk_fma_f32 v[12:13], v[12:13], v[144:145], v[140:141]
	v_pk_fma_f32 v[10:11], v[10:11], v[146:147], v[152:153]
	v_mov_b32_e32 v138, v70
	global_load_dwordx4 v[148:151], v[150:151], off offset:256
	v_mov_b32_e32 v139, v73
	v_mov_b32_e32 v140, v67
	v_mov_b32_e32 v141, v68
	v_mov_b32_e32 v152, v66
	v_mov_b32_e32 v153, v69
	v_pk_add_f32 v[76:77], v[76:77], v[138:139]
	v_pk_add_f32 v[138:139], v[140:141], v[152:153]
	v_add_f32_e32 v140, v76, v77
	v_pk_add_f32 v[76:77], v[138:139], v[138:139] op_sel_hi:[0,1]
	v_add_f32_e32 v139, 0, v140
	v_add_f32_e32 v141, v78, v79
	v_add_f32_e32 v153, v80, v81
	v_mov_b32_e32 v76, v54
	v_mov_b32_e32 v138, v55
	v_mov_b32_e32 v140, v56
	v_mov_b32_e32 v152, v57
	v_pk_add_f32 v[76:77], v[76:77], v[138:139]
	v_pk_add_f32 v[138:139], v[140:141], v[152:153]
	v_cndmask_b32_e32 v74, v75, v74, vcc
	v_pk_add_f32 v[76:77], v[76:77], v[138:139]
	v_lshlrev_b32_e32 v74, 2, v74
	v_add_f32_e32 v76, v76, v77
	ds_bpermute_b32 v77, v74, v76
	v_xor_b32_e32 v138, 32, v75
	v_cmp_lt_i32_e32 vcc, v138, v156
	s_waitcnt lgkmcnt(0)
	v_add_f32_e32 v76, v76, v77
	v_cndmask_b32_e32 v75, v75, v138, vcc
	v_lshlrev_b32_e32 v75, 2, v75
	ds_bpermute_b32 v77, v75, v76
	s_waitcnt lgkmcnt(0)
	v_add_f32_e32 v77, v76, v77
	v_fmamk_f32 v138, v77, 0xbc800000, v73
	v_fmamk_f32 v140, v77, 0xbc800000, v71
	v_fmamk_f32 v152, v77, 0xbc800000, v69
	v_fmamk_f32 v156, v77, 0xbc800000, v67
	v_fmamk_f32 v76, v77, 0xbc800000, v72
	v_fmamk_f32 v139, v77, 0xbc800000, v70
	v_fmamk_f32 v141, v77, 0xbc800000, v68
	v_fmamk_f32 v153, v77, 0xbc800000, v66
	v_fmamk_f32 v158, v77, 0xbc800000, v81
	v_fmamk_f32 v162, v77, 0xbc800000, v79
	v_mul_f32_e32 v140, v140, v140
	v_mul_f32_e32 v138, v138, v138
	v_mul_f32_e32 v156, v156, v156
	v_mul_f32_e32 v152, v152, v152
	v_fmamk_f32 v157, v77, 0xbc800000, v80
	v_fmamk_f32 v159, v77, 0xbc800000, v78
	v_fmamk_f32 v164, v77, 0xbc800000, v57
	v_fmamk_f32 v166, v77, 0xbc800000, v55
	v_mul_f32_e32 v162, v162, v162
	v_mul_f32_e32 v158, v158, v158
	v_fmac_f32_e32 v140, v139, v139
	v_fmac_f32_e32 v138, v76, v76
	v_fmac_f32_e32 v156, v153, v153
	v_fmac_f32_e32 v152, v141, v141
	v_fmamk_f32 v163, v77, 0xbc800000, v56
	v_fmamk_f32 v165, v77, 0xbc800000, v54
	v_mul_f32_e32 v166, v166, v166
	v_mul_f32_e32 v164, v164, v164
	v_fmac_f32_e32 v162, v159, v159
	v_fmac_f32_e32 v158, v157, v157
	v_add_f32_e32 v76, v140, v138
	v_add_f32_e32 v138, v156, v152
	v_fmac_f32_e32 v166, v165, v165
	v_fmac_f32_e32 v164, v163, v163
	v_add_f32_e32 v139, v162, v158
	v_add_f32_e32 v76, v76, v138
	v_add_f32_e32 v140, v166, v164
	v_add_f32_e32 v76, v139, v76
	v_add_f32_e32 v138, v140, v76
	ds_bpermute_b32 v139, v74, v138
	v_and_b32_e32 v76, 63, v160
	v_cmp_gt_u32_e32 vcc, 16, v76
	s_waitcnt vmcnt(0)
	v_lshlrev_b32_e32 v140, 16, v148
	s_waitcnt lgkmcnt(0)
	v_add_f32_e32 v138, v138, v139
	v_and_b32_e32 v141, 0xffff0000, v148
	v_lshlrev_b32_e32 v148, 16, v149
	v_and_b32_e32 v149, 0xffff0000, v149
	v_lshlrev_b32_e32 v152, 16, v150
	v_and_b32_e32 v153, 0xffff0000, v150
	v_lshlrev_b32_e32 v150, 16, v151
	v_and_b32_e32 v151, 0xffff0000, v151
	ds_bpermute_b32 v139, v75, v138
	v_pk_mul_f32 v[140:141], v[140:141], s[0:1] op_sel_hi:[1,0]
	v_pk_mul_f32 v[148:149], v[148:149], s[0:1] op_sel_hi:[1,0]
	v_pk_mul_f32 v[152:153], v[152:153], s[0:1] op_sel_hi:[1,0]
	v_pk_mul_f32 v[150:151], v[150:151], s[0:1] op_sel_hi:[1,0]
	v_pk_fma_f32 v[8:9], v[8:9], v[136:137], v[148:149]
	v_pk_fma_f32 v[6:7], v[6:7], v[142:143], v[140:141]
	v_pk_fma_f32 v[4:5], v[4:5], v[144:145], v[150:151]
	v_pk_fma_f32 v[2:3], v[2:3], v[146:147], v[152:153]
	s_lshl_b32 s0, s13, 3
	s_add_i32 s4, s0, 0
	s_and_saveexec_b64 s[0:1], vcc
	s_cbranch_execz .LBB0_1924
	s_lshl_b32 s5, s37, 11
	s_add_i32 s5, s4, s5
	v_mul_f32_e32 v136, 0x3c800000, v77
	v_lshl_add_u32 v77, v161, 5, s5
	s_waitcnt lgkmcnt(0)
	v_add_f32_e32 v137, v138, v139
	ds_write_b64 v77, v[136:137]
